# latent WKV scan: compute loop fully unrolled with LDS operands prefetched two steps ahead (three register sets), no other change
# speedup vs baseline: 1.0159x; 1.0159x over previous
.LBB0_185:
	s_and_saveexec_b64 s[20:21], s[40:41]
	s_cbranch_execz .LBB0_194
	ds_read_b128 v[2:5], v228
	ds_read_b128 v[6:9], v228 offset:4096
	ds_read_b128 v[10:13], v228 offset:8192
	ds_read_b128 v[14:17], v228 offset:12288
	ds_read_b128 v[18:21], v228 offset:16384
	ds_read_b32 v22, v229 offset:40960
	ds_read_b128 v[24:27], v228 offset:256
	ds_read_b128 v[28:31], v228 offset:4352
	ds_read_b128 v[32:35], v228 offset:8448
	ds_read_b128 v[36:39], v228 offset:12544
	ds_read_b128 v[40:43], v228 offset:16640
	ds_read_b32 v44, v229 offset:41024
	s_waitcnt vmcnt(0)
	s_waitcnt lgkmcnt(6)
	v_pk_mul_f32 v[80:81], v[52:53], v[8:9]
	v_pk_mul_f32 v[76:77], v[14:15], v[22:23] op_sel_hi:[1,0]
	v_pk_fma_f32 v[80:81], v[50:51], v[6:7], v[80:81]
	v_pk_mul_f32 v[78:79], v[16:17], v[22:23] op_sel_hi:[1,0]
	v_add_f32_e32 v80, v80, v81
	v_pk_fma_f32 v[76:77], v[50:51], v[2:3], v[76:77]
	v_pk_fma_f32 v[78:79], v[52:53], v[4:5], v[78:79]
	v_add_f32_dpp v80, v80, v80 quad_perm:[1,0,3,2] row_mask:0xf bank_mask:0xf bound_ctrl:1
	ds_read_b128 v[54:57], v228 offset:512
	ds_read_b128 v[58:61], v228 offset:4608
	v_add_f32_dpp v80, v80, v80 quad_perm:[2,3,0,1] row_mask:0xf bank_mask:0xf bound_ctrl:1
	ds_read_b128 v[62:65], v228 offset:8704
	ds_read_b128 v[66:69], v228 offset:12800
	v_add_f32_dpp v80, v80, v80 row_half_mirror row_mask:0xf bank_mask:0xf bound_ctrl:1
	ds_read_b128 v[70:73], v228 offset:16896
	ds_read_b32 v74, v229 offset:41088
	v_add_f32_dpp v80, v80, v80 row_mirror row_mask:0xf bank_mask:0xf bound_ctrl:1
	v_pk_fma_f32 v[52:53], v[12:13], v[80:81], v[78:79] op_sel_hi:[1,0,1] neg_lo:[0,1,0] neg_hi:[0,1,0]
	v_pk_fma_f32 v[50:51], v[10:11], v[80:81], v[76:77] op_sel_hi:[1,0,1] neg_lo:[0,1,0] neg_hi:[0,1,0]
	v_pk_mul_f32 v[82:83], v[20:21], v[52:53]
	s_nop 0
	v_pk_fma_f32 v[82:83], v[18:19], v[50:51], v[82:83]
	s_nop 0
	v_add_f32_e32 v82, v82, v83
	ds_write_b32 v244, v82
	s_waitcnt lgkmcnt(7)
	v_pk_mul_f32 v[80:81], v[52:53], v[30:31]
	v_pk_mul_f32 v[76:77], v[36:37], v[44:45] op_sel_hi:[1,0]
	v_pk_fma_f32 v[80:81], v[50:51], v[28:29], v[80:81]
	v_pk_mul_f32 v[78:79], v[38:39], v[44:45] op_sel_hi:[1,0]
	v_add_f32_e32 v80, v80, v81
	v_pk_fma_f32 v[76:77], v[50:51], v[24:25], v[76:77]
	v_pk_fma_f32 v[78:79], v[52:53], v[26:27], v[78:79]
	v_add_f32_dpp v80, v80, v80 quad_perm:[1,0,3,2] row_mask:0xf bank_mask:0xf bound_ctrl:1
	ds_read_b128 v[2:5], v228 offset:768
	ds_read_b128 v[6:9], v228 offset:4864
	v_add_f32_dpp v80, v80, v80 quad_perm:[2,3,0,1] row_mask:0xf bank_mask:0xf bound_ctrl:1
	ds_read_b128 v[10:13], v228 offset:8960
	ds_read_b128 v[14:17], v228 offset:13056
	v_add_f32_dpp v80, v80, v80 row_half_mirror row_mask:0xf bank_mask:0xf bound_ctrl:1
	ds_read_b128 v[18:21], v228 offset:17152
	ds_read_b32 v22, v229 offset:41152
	v_add_f32_dpp v80, v80, v80 row_mirror row_mask:0xf bank_mask:0xf bound_ctrl:1
	v_pk_fma_f32 v[52:53], v[34:35], v[80:81], v[78:79] op_sel_hi:[1,0,1] neg_lo:[0,1,0] neg_hi:[0,1,0]
	v_pk_fma_f32 v[50:51], v[32:33], v[80:81], v[76:77] op_sel_hi:[1,0,1] neg_lo:[0,1,0] neg_hi:[0,1,0]
	v_pk_mul_f32 v[82:83], v[42:43], v[52:53]
	s_nop 0
	v_pk_fma_f32 v[82:83], v[40:41], v[50:51], v[82:83]
	s_nop 0
	v_add_f32_e32 v82, v82, v83
	ds_write_b32 v244, v82 offset:256
	s_waitcnt lgkmcnt(8)
	v_pk_mul_f32 v[80:81], v[52:53], v[60:61]
	v_pk_mul_f32 v[76:77], v[66:67], v[74:75] op_sel_hi:[1,0]
	v_pk_fma_f32 v[80:81], v[50:51], v[58:59], v[80:81]
	v_pk_mul_f32 v[78:79], v[68:69], v[74:75] op_sel_hi:[1,0]
	v_add_f32_e32 v80, v80, v81
	v_pk_fma_f32 v[76:77], v[50:51], v[54:55], v[76:77]
	v_pk_fma_f32 v[78:79], v[52:53], v[56:57], v[78:79]
	v_add_f32_dpp v80, v80, v80 quad_perm:[1,0,3,2] row_mask:0xf bank_mask:0xf bound_ctrl:1
	ds_read_b128 v[24:27], v228 offset:1024
	ds_read_b128 v[28:31], v228 offset:5120
	v_add_f32_dpp v80, v80, v80 quad_perm:[2,3,0,1] row_mask:0xf bank_mask:0xf bound_ctrl:1
	ds_read_b128 v[32:35], v228 offset:9216
	ds_read_b128 v[36:39], v228 offset:13312
	v_add_f32_dpp v80, v80, v80 row_half_mirror row_mask:0xf bank_mask:0xf bound_ctrl:1
	ds_read_b128 v[40:43], v228 offset:17408
	ds_read_b32 v44, v229 offset:41216
	v_add_f32_dpp v80, v80, v80 row_mirror row_mask:0xf bank_mask:0xf bound_ctrl:1
	v_pk_fma_f32 v[52:53], v[64:65], v[80:81], v[78:79] op_sel_hi:[1,0,1] neg_lo:[0,1,0] neg_hi:[0,1,0]
	v_pk_fma_f32 v[50:51], v[62:63], v[80:81], v[76:77] op_sel_hi:[1,0,1] neg_lo:[0,1,0] neg_hi:[0,1,0]
	v_pk_mul_f32 v[82:83], v[72:73], v[52:53]
	s_nop 0
	v_pk_fma_f32 v[82:83], v[70:71], v[50:51], v[82:83]
	s_nop 0
	v_add_f32_e32 v82, v82, v83
	ds_write_b32 v244, v82 offset:512
	s_waitcnt lgkmcnt(8)
	v_pk_mul_f32 v[80:81], v[52:53], v[8:9]
	v_pk_mul_f32 v[76:77], v[14:15], v[22:23] op_sel_hi:[1,0]
	v_pk_fma_f32 v[80:81], v[50:51], v[6:7], v[80:81]
	v_pk_mul_f32 v[78:79], v[16:17], v[22:23] op_sel_hi:[1,0]
	v_add_f32_e32 v80, v80, v81
	v_pk_fma_f32 v[76:77], v[50:51], v[2:3], v[76:77]
	v_pk_fma_f32 v[78:79], v[52:53], v[4:5], v[78:79]
	v_add_f32_dpp v80, v80, v80 quad_perm:[1,0,3,2] row_mask:0xf bank_mask:0xf bound_ctrl:1
	ds_read_b128 v[54:57], v228 offset:1280
	ds_read_b128 v[58:61], v228 offset:5376
	v_add_f32_dpp v80, v80, v80 quad_perm:[2,3,0,1] row_mask:0xf bank_mask:0xf bound_ctrl:1
	ds_read_b128 v[62:65], v228 offset:9472
	ds_read_b128 v[66:69], v228 offset:13568
	v_add_f32_dpp v80, v80, v80 row_half_mirror row_mask:0xf bank_mask:0xf bound_ctrl:1
	ds_read_b128 v[70:73], v228 offset:17664
	ds_read_b32 v74, v229 offset:41280
	v_add_f32_dpp v80, v80, v80 row_mirror row_mask:0xf bank_mask:0xf bound_ctrl:1
	v_pk_fma_f32 v[52:53], v[12:13], v[80:81], v[78:79] op_sel_hi:[1,0,1] neg_lo:[0,1,0] neg_hi:[0,1,0]
	v_pk_fma_f32 v[50:51], v[10:11], v[80:81], v[76:77] op_sel_hi:[1,0,1] neg_lo:[0,1,0] neg_hi:[0,1,0]
	v_pk_mul_f32 v[82:83], v[20:21], v[52:53]
	s_nop 0
	v_pk_fma_f32 v[82:83], v[18:19], v[50:51], v[82:83]
	s_nop 0
	v_add_f32_e32 v82, v82, v83
	ds_write_b32 v244, v82 offset:768
	s_waitcnt lgkmcnt(8)
	v_pk_mul_f32 v[80:81], v[52:53], v[30:31]
	v_pk_mul_f32 v[76:77], v[36:37], v[44:45] op_sel_hi:[1,0]
	v_pk_fma_f32 v[80:81], v[50:51], v[28:29], v[80:81]
	v_pk_mul_f32 v[78:79], v[38:39], v[44:45] op_sel_hi:[1,0]
	v_add_f32_e32 v80, v80, v81
	v_pk_fma_f32 v[76:77], v[50:51], v[24:25], v[76:77]
	v_pk_fma_f32 v[78:79], v[52:53], v[26:27], v[78:79]
	v_add_f32_dpp v80, v80, v80 quad_perm:[1,0,3,2] row_mask:0xf bank_mask:0xf bound_ctrl:1
	ds_read_b128 v[2:5], v228 offset:1536
	ds_read_b128 v[6:9], v228 offset:5632
	v_add_f32_dpp v80, v80, v80 quad_perm:[2,3,0,1] row_mask:0xf bank_mask:0xf bound_ctrl:1
	ds_read_b128 v[10:13], v228 offset:9728
	ds_read_b128 v[14:17], v228 offset:13824
	v_add_f32_dpp v80, v80, v80 row_half_mirror row_mask:0xf bank_mask:0xf bound_ctrl:1
	ds_read_b128 v[18:21], v228 offset:17920
	ds_read_b32 v22, v229 offset:41344
	v_add_f32_dpp v80, v80, v80 row_mirror row_mask:0xf bank_mask:0xf bound_ctrl:1
	v_pk_fma_f32 v[52:53], v[34:35], v[80:81], v[78:79] op_sel_hi:[1,0,1] neg_lo:[0,1,0] neg_hi:[0,1,0]
	v_pk_fma_f32 v[50:51], v[32:33], v[80:81], v[76:77] op_sel_hi:[1,0,1] neg_lo:[0,1,0] neg_hi:[0,1,0]
	v_pk_mul_f32 v[82:83], v[42:43], v[52:53]
	s_nop 0
	v_pk_fma_f32 v[82:83], v[40:41], v[50:51], v[82:83]
	s_nop 0
	v_add_f32_e32 v82, v82, v83
	ds_write_b32 v244, v82 offset:1024
	s_waitcnt lgkmcnt(8)
	v_pk_mul_f32 v[80:81], v[52:53], v[60:61]
	v_pk_mul_f32 v[76:77], v[66:67], v[74:75] op_sel_hi:[1,0]
	v_pk_fma_f32 v[80:81], v[50:51], v[58:59], v[80:81]
	v_pk_mul_f32 v[78:79], v[68:69], v[74:75] op_sel_hi:[1,0]
	v_add_f32_e32 v80, v80, v81
	v_pk_fma_f32 v[76:77], v[50:51], v[54:55], v[76:77]
	v_pk_fma_f32 v[78:79], v[52:53], v[56:57], v[78:79]
	v_add_f32_dpp v80, v80, v80 quad_perm:[1,0,3,2] row_mask:0xf bank_mask:0xf bound_ctrl:1
	ds_read_b128 v[24:27], v228 offset:1792
	ds_read_b128 v[28:31], v228 offset:5888
	v_add_f32_dpp v80, v80, v80 quad_perm:[2,3,0,1] row_mask:0xf bank_mask:0xf bound_ctrl:1
	ds_read_b128 v[32:35], v228 offset:9984
	ds_read_b128 v[36:39], v228 offset:14080
	v_add_f32_dpp v80, v80, v80 row_half_mirror row_mask:0xf bank_mask:0xf bound_ctrl:1
	ds_read_b128 v[40:43], v228 offset:18176
	ds_read_b32 v44, v229 offset:41408
	v_add_f32_dpp v80, v80, v80 row_mirror row_mask:0xf bank_mask:0xf bound_ctrl:1
	v_pk_fma_f32 v[52:53], v[64:65], v[80:81], v[78:79] op_sel_hi:[1,0,1] neg_lo:[0,1,0] neg_hi:[0,1,0]
	v_pk_fma_f32 v[50:51], v[62:63], v[80:81], v[76:77] op_sel_hi:[1,0,1] neg_lo:[0,1,0] neg_hi:[0,1,0]
	v_pk_mul_f32 v[82:83], v[72:73], v[52:53]
	s_nop 0
	v_pk_fma_f32 v[82:83], v[70:71], v[50:51], v[82:83]
	s_nop 0
	v_add_f32_e32 v82, v82, v83
	ds_write_b32 v244, v82 offset:1280
	s_waitcnt lgkmcnt(8)
	v_pk_mul_f32 v[80:81], v[52:53], v[8:9]
	v_pk_mul_f32 v[76:77], v[14:15], v[22:23] op_sel_hi:[1,0]
	v_pk_fma_f32 v[80:81], v[50:51], v[6:7], v[80:81]
	v_pk_mul_f32 v[78:79], v[16:17], v[22:23] op_sel_hi:[1,0]
	v_add_f32_e32 v80, v80, v81
	v_pk_fma_f32 v[76:77], v[50:51], v[2:3], v[76:77]
	v_pk_fma_f32 v[78:79], v[52:53], v[4:5], v[78:79]
	v_add_f32_dpp v80, v80, v80 quad_perm:[1,0,3,2] row_mask:0xf bank_mask:0xf bound_ctrl:1
	ds_read_b128 v[54:57], v228 offset:2048
	ds_read_b128 v[58:61], v228 offset:6144
	v_add_f32_dpp v80, v80, v80 quad_perm:[2,3,0,1] row_mask:0xf bank_mask:0xf bound_ctrl:1
	ds_read_b128 v[62:65], v228 offset:10240
	ds_read_b128 v[66:69], v228 offset:14336
	v_add_f32_dpp v80, v80, v80 row_half_mirror row_mask:0xf bank_mask:0xf bound_ctrl:1
	ds_read_b128 v[70:73], v228 offset:18432
	ds_read_b32 v74, v229 offset:41472
	v_add_f32_dpp v80, v80, v80 row_mirror row_mask:0xf bank_mask:0xf bound_ctrl:1
	v_pk_fma_f32 v[52:53], v[12:13], v[80:81], v[78:79] op_sel_hi:[1,0,1] neg_lo:[0,1,0] neg_hi:[0,1,0]
	v_pk_fma_f32 v[50:51], v[10:11], v[80:81], v[76:77] op_sel_hi:[1,0,1] neg_lo:[0,1,0] neg_hi:[0,1,0]
	v_pk_mul_f32 v[82:83], v[20:21], v[52:53]
	s_nop 0
	v_pk_fma_f32 v[82:83], v[18:19], v[50:51], v[82:83]
	s_nop 0
	v_add_f32_e32 v82, v82, v83
	ds_write_b32 v244, v82 offset:1536
	s_waitcnt lgkmcnt(8)
	v_pk_mul_f32 v[80:81], v[52:53], v[30:31]
	v_pk_mul_f32 v[76:77], v[36:37], v[44:45] op_sel_hi:[1,0]
	v_pk_fma_f32 v[80:81], v[50:51], v[28:29], v[80:81]
	v_pk_mul_f32 v[78:79], v[38:39], v[44:45] op_sel_hi:[1,0]
	v_add_f32_e32 v80, v80, v81
	v_pk_fma_f32 v[76:77], v[50:51], v[24:25], v[76:77]
	v_pk_fma_f32 v[78:79], v[52:53], v[26:27], v[78:79]
	v_add_f32_dpp v80, v80, v80 quad_perm:[1,0,3,2] row_mask:0xf bank_mask:0xf bound_ctrl:1
	ds_read_b128 v[2:5], v228 offset:2304
	ds_read_b128 v[6:9], v228 offset:6400
	v_add_f32_dpp v80, v80, v80 quad_perm:[2,3,0,1] row_mask:0xf bank_mask:0xf bound_ctrl:1
	ds_read_b128 v[10:13], v228 offset:10496
	ds_read_b128 v[14:17], v228 offset:14592
	v_add_f32_dpp v80, v80, v80 row_half_mirror row_mask:0xf bank_mask:0xf bound_ctrl:1
	ds_read_b128 v[18:21], v228 offset:18688
	ds_read_b32 v22, v229 offset:41536
	v_add_f32_dpp v80, v80, v80 row_mirror row_mask:0xf bank_mask:0xf bound_ctrl:1
	v_pk_fma_f32 v[52:53], v[34:35], v[80:81], v[78:79] op_sel_hi:[1,0,1] neg_lo:[0,1,0] neg_hi:[0,1,0]
	v_pk_fma_f32 v[50:51], v[32:33], v[80:81], v[76:77] op_sel_hi:[1,0,1] neg_lo:[0,1,0] neg_hi:[0,1,0]
	v_pk_mul_f32 v[82:83], v[42:43], v[52:53]
	s_nop 0
	v_pk_fma_f32 v[82:83], v[40:41], v[50:51], v[82:83]
	s_nop 0
	v_add_f32_e32 v82, v82, v83
	ds_write_b32 v244, v82 offset:1792
	s_waitcnt lgkmcnt(8)
	v_pk_mul_f32 v[80:81], v[52:53], v[60:61]
	v_pk_mul_f32 v[76:77], v[66:67], v[74:75] op_sel_hi:[1,0]
	v_pk_fma_f32 v[80:81], v[50:51], v[58:59], v[80:81]
	v_pk_mul_f32 v[78:79], v[68:69], v[74:75] op_sel_hi:[1,0]
	v_add_f32_e32 v80, v80, v81
	v_pk_fma_f32 v[76:77], v[50:51], v[54:55], v[76:77]
	v_pk_fma_f32 v[78:79], v[52:53], v[56:57], v[78:79]
	v_add_f32_dpp v80, v80, v80 quad_perm:[1,0,3,2] row_mask:0xf bank_mask:0xf bound_ctrl:1
	ds_read_b128 v[24:27], v228 offset:2560
	ds_read_b128 v[28:31], v228 offset:6656
	v_add_f32_dpp v80, v80, v80 quad_perm:[2,3,0,1] row_mask:0xf bank_mask:0xf bound_ctrl:1
	ds_read_b128 v[32:35], v228 offset:10752
	ds_read_b128 v[36:39], v228 offset:14848
	v_add_f32_dpp v80, v80, v80 row_half_mirror row_mask:0xf bank_mask:0xf bound_ctrl:1
	ds_read_b128 v[40:43], v228 offset:18944
	ds_read_b32 v44, v229 offset:41600
	v_add_f32_dpp v80, v80, v80 row_mirror row_mask:0xf bank_mask:0xf bound_ctrl:1
	v_pk_fma_f32 v[52:53], v[64:65], v[80:81], v[78:79] op_sel_hi:[1,0,1] neg_lo:[0,1,0] neg_hi:[0,1,0]
	v_pk_fma_f32 v[50:51], v[62:63], v[80:81], v[76:77] op_sel_hi:[1,0,1] neg_lo:[0,1,0] neg_hi:[0,1,0]
	v_pk_mul_f32 v[82:83], v[72:73], v[52:53]
	s_nop 0
	v_pk_fma_f32 v[82:83], v[70:71], v[50:51], v[82:83]
	s_nop 0
	v_add_f32_e32 v82, v82, v83
	ds_write_b32 v244, v82 offset:2048
	s_waitcnt lgkmcnt(8)
	v_pk_mul_f32 v[80:81], v[52:53], v[8:9]
	v_pk_mul_f32 v[76:77], v[14:15], v[22:23] op_sel_hi:[1,0]
	v_pk_fma_f32 v[80:81], v[50:51], v[6:7], v[80:81]
	v_pk_mul_f32 v[78:79], v[16:17], v[22:23] op_sel_hi:[1,0]
	v_add_f32_e32 v80, v80, v81
	v_pk_fma_f32 v[76:77], v[50:51], v[2:3], v[76:77]
	v_pk_fma_f32 v[78:79], v[52:53], v[4:5], v[78:79]
	v_add_f32_dpp v80, v80, v80 quad_perm:[1,0,3,2] row_mask:0xf bank_mask:0xf bound_ctrl:1
	ds_read_b128 v[54:57], v228 offset:2816
	ds_read_b128 v[58:61], v228 offset:6912
	v_add_f32_dpp v80, v80, v80 quad_perm:[2,3,0,1] row_mask:0xf bank_mask:0xf bound_ctrl:1
	ds_read_b128 v[62:65], v228 offset:11008
	ds_read_b128 v[66:69], v228 offset:15104
	v_add_f32_dpp v80, v80, v80 row_half_mirror row_mask:0xf bank_mask:0xf bound_ctrl:1
	ds_read_b128 v[70:73], v228 offset:19200
	ds_read_b32 v74, v229 offset:41664
	v_add_f32_dpp v80, v80, v80 row_mirror row_mask:0xf bank_mask:0xf bound_ctrl:1
	v_pk_fma_f32 v[52:53], v[12:13], v[80:81], v[78:79] op_sel_hi:[1,0,1] neg_lo:[0,1,0] neg_hi:[0,1,0]
	v_pk_fma_f32 v[50:51], v[10:11], v[80:81], v[76:77] op_sel_hi:[1,0,1] neg_lo:[0,1,0] neg_hi:[0,1,0]
	v_pk_mul_f32 v[82:83], v[20:21], v[52:53]
	s_nop 0
	v_pk_fma_f32 v[82:83], v[18:19], v[50:51], v[82:83]
	s_nop 0
	v_add_f32_e32 v82, v82, v83
	ds_write_b32 v244, v82 offset:2304
	s_waitcnt lgkmcnt(8)
	v_pk_mul_f32 v[80:81], v[52:53], v[30:31]
	v_pk_mul_f32 v[76:77], v[36:37], v[44:45] op_sel_hi:[1,0]
	v_pk_fma_f32 v[80:81], v[50:51], v[28:29], v[80:81]
	v_pk_mul_f32 v[78:79], v[38:39], v[44:45] op_sel_hi:[1,0]
	v_add_f32_e32 v80, v80, v81
	v_pk_fma_f32 v[76:77], v[50:51], v[24:25], v[76:77]
	v_pk_fma_f32 v[78:79], v[52:53], v[26:27], v[78:79]
	v_add_f32_dpp v80, v80, v80 quad_perm:[1,0,3,2] row_mask:0xf bank_mask:0xf bound_ctrl:1
	ds_read_b128 v[2:5], v228 offset:3072
	ds_read_b128 v[6:9], v228 offset:7168
	v_add_f32_dpp v80, v80, v80 quad_perm:[2,3,0,1] row_mask:0xf bank_mask:0xf bound_ctrl:1
	ds_read_b128 v[10:13], v228 offset:11264
	ds_read_b128 v[14:17], v228 offset:15360
	v_add_f32_dpp v80, v80, v80 row_half_mirror row_mask:0xf bank_mask:0xf bound_ctrl:1
	ds_read_b128 v[18:21], v228 offset:19456
	ds_read_b32 v22, v229 offset:41728
	v_add_f32_dpp v80, v80, v80 row_mirror row_mask:0xf bank_mask:0xf bound_ctrl:1
	v_pk_fma_f32 v[52:53], v[34:35], v[80:81], v[78:79] op_sel_hi:[1,0,1] neg_lo:[0,1,0] neg_hi:[0,1,0]
	v_pk_fma_f32 v[50:51], v[32:33], v[80:81], v[76:77] op_sel_hi:[1,0,1] neg_lo:[0,1,0] neg_hi:[0,1,0]
	v_pk_mul_f32 v[82:83], v[42:43], v[52:53]
	s_nop 0
	v_pk_fma_f32 v[82:83], v[40:41], v[50:51], v[82:83]
	s_nop 0
	v_add_f32_e32 v82, v82, v83
	ds_write_b32 v244, v82 offset:2560
	s_waitcnt lgkmcnt(8)
	v_pk_mul_f32 v[80:81], v[52:53], v[60:61]
	v_pk_mul_f32 v[76:77], v[66:67], v[74:75] op_sel_hi:[1,0]
	v_pk_fma_f32 v[80:81], v[50:51], v[58:59], v[80:81]
	v_pk_mul_f32 v[78:79], v[68:69], v[74:75] op_sel_hi:[1,0]
	v_add_f32_e32 v80, v80, v81
	v_pk_fma_f32 v[76:77], v[50:51], v[54:55], v[76:77]
	v_pk_fma_f32 v[78:79], v[52:53], v[56:57], v[78:79]
	v_add_f32_dpp v80, v80, v80 quad_perm:[1,0,3,2] row_mask:0xf bank_mask:0xf bound_ctrl:1
	ds_read_b128 v[24:27], v228 offset:3328
	ds_read_b128 v[28:31], v228 offset:7424
	v_add_f32_dpp v80, v80, v80 quad_perm:[2,3,0,1] row_mask:0xf bank_mask:0xf bound_ctrl:1
	ds_read_b128 v[32:35], v228 offset:11520
	ds_read_b128 v[36:39], v228 offset:15616
	v_add_f32_dpp v80, v80, v80 row_half_mirror row_mask:0xf bank_mask:0xf bound_ctrl:1
	ds_read_b128 v[40:43], v228 offset:19712
	ds_read_b32 v44, v229 offset:41792
	v_add_f32_dpp v80, v80, v80 row_mirror row_mask:0xf bank_mask:0xf bound_ctrl:1
	v_pk_fma_f32 v[52:53], v[64:65], v[80:81], v[78:79] op_sel_hi:[1,0,1] neg_lo:[0,1,0] neg_hi:[0,1,0]
	v_pk_fma_f32 v[50:51], v[62:63], v[80:81], v[76:77] op_sel_hi:[1,0,1] neg_lo:[0,1,0] neg_hi:[0,1,0]
	v_pk_mul_f32 v[82:83], v[72:73], v[52:53]
	s_nop 0
	v_pk_fma_f32 v[82:83], v[70:71], v[50:51], v[82:83]
	s_nop 0
	v_add_f32_e32 v82, v82, v83
	ds_write_b32 v244, v82 offset:2816
	s_waitcnt lgkmcnt(8)
	v_pk_mul_f32 v[80:81], v[52:53], v[8:9]
	v_pk_mul_f32 v[76:77], v[14:15], v[22:23] op_sel_hi:[1,0]
	v_pk_fma_f32 v[80:81], v[50:51], v[6:7], v[80:81]
	v_pk_mul_f32 v[78:79], v[16:17], v[22:23] op_sel_hi:[1,0]
	v_add_f32_e32 v80, v80, v81
	v_pk_fma_f32 v[76:77], v[50:51], v[2:3], v[76:77]
	v_pk_fma_f32 v[78:79], v[52:53], v[4:5], v[78:79]
	v_add_f32_dpp v80, v80, v80 quad_perm:[1,0,3,2] row_mask:0xf bank_mask:0xf bound_ctrl:1
	ds_read_b128 v[54:57], v228 offset:3584
	ds_read_b128 v[58:61], v228 offset:7680
	v_add_f32_dpp v80, v80, v80 quad_perm:[2,3,0,1] row_mask:0xf bank_mask:0xf bound_ctrl:1
	ds_read_b128 v[62:65], v228 offset:11776
	ds_read_b128 v[66:69], v228 offset:15872
	v_add_f32_dpp v80, v80, v80 row_half_mirror row_mask:0xf bank_mask:0xf bound_ctrl:1
	ds_read_b128 v[70:73], v228 offset:19968
	ds_read_b32 v74, v229 offset:41856
	v_add_f32_dpp v80, v80, v80 row_mirror row_mask:0xf bank_mask:0xf bound_ctrl:1
	v_pk_fma_f32 v[52:53], v[12:13], v[80:81], v[78:79] op_sel_hi:[1,0,1] neg_lo:[0,1,0] neg_hi:[0,1,0]
	v_pk_fma_f32 v[50:51], v[10:11], v[80:81], v[76:77] op_sel_hi:[1,0,1] neg_lo:[0,1,0] neg_hi:[0,1,0]
	v_pk_mul_f32 v[82:83], v[20:21], v[52:53]
	s_nop 0
	v_pk_fma_f32 v[82:83], v[18:19], v[50:51], v[82:83]
	s_nop 0
	v_add_f32_e32 v82, v82, v83
	ds_write_b32 v244, v82 offset:3072
	s_waitcnt lgkmcnt(8)
	v_pk_mul_f32 v[80:81], v[52:53], v[30:31]
	v_pk_mul_f32 v[76:77], v[36:37], v[44:45] op_sel_hi:[1,0]
	v_pk_fma_f32 v[80:81], v[50:51], v[28:29], v[80:81]
	v_pk_mul_f32 v[78:79], v[38:39], v[44:45] op_sel_hi:[1,0]
	v_add_f32_e32 v80, v80, v81
	v_pk_fma_f32 v[76:77], v[50:51], v[24:25], v[76:77]
	v_pk_fma_f32 v[78:79], v[52:53], v[26:27], v[78:79]
	v_add_f32_dpp v80, v80, v80 quad_perm:[1,0,3,2] row_mask:0xf bank_mask:0xf bound_ctrl:1
	ds_read_b128 v[2:5], v228 offset:3840
	ds_read_b128 v[6:9], v228 offset:7936
	v_add_f32_dpp v80, v80, v80 quad_perm:[2,3,0,1] row_mask:0xf bank_mask:0xf bound_ctrl:1
	ds_read_b128 v[10:13], v228 offset:12032
	ds_read_b128 v[14:17], v228 offset:16128
	v_add_f32_dpp v80, v80, v80 row_half_mirror row_mask:0xf bank_mask:0xf bound_ctrl:1
	ds_read_b128 v[18:21], v228 offset:20224
	ds_read_b32 v22, v229 offset:41920
	v_add_f32_dpp v80, v80, v80 row_mirror row_mask:0xf bank_mask:0xf bound_ctrl:1
	v_pk_fma_f32 v[52:53], v[34:35], v[80:81], v[78:79] op_sel_hi:[1,0,1] neg_lo:[0,1,0] neg_hi:[0,1,0]
	v_pk_fma_f32 v[50:51], v[32:33], v[80:81], v[76:77] op_sel_hi:[1,0,1] neg_lo:[0,1,0] neg_hi:[0,1,0]
	v_pk_mul_f32 v[82:83], v[42:43], v[52:53]
	s_nop 0
	v_pk_fma_f32 v[82:83], v[40:41], v[50:51], v[82:83]
	s_nop 0
	v_add_f32_e32 v82, v82, v83
	ds_write_b32 v244, v82 offset:3328
	s_waitcnt lgkmcnt(8)
	v_pk_mul_f32 v[80:81], v[52:53], v[60:61]
	v_pk_mul_f32 v[76:77], v[66:67], v[74:75] op_sel_hi:[1,0]
	v_pk_fma_f32 v[80:81], v[50:51], v[58:59], v[80:81]
	v_pk_mul_f32 v[78:79], v[68:69], v[74:75] op_sel_hi:[1,0]
	v_add_f32_e32 v80, v80, v81
	v_pk_fma_f32 v[76:77], v[50:51], v[54:55], v[76:77]
	v_pk_fma_f32 v[78:79], v[52:53], v[56:57], v[78:79]
	v_add_f32_dpp v80, v80, v80 quad_perm:[1,0,3,2] row_mask:0xf bank_mask:0xf bound_ctrl:1
	s_nop 1
	v_add_f32_dpp v80, v80, v80 quad_perm:[2,3,0,1] row_mask:0xf bank_mask:0xf bound_ctrl:1
	s_nop 1
	v_add_f32_dpp v80, v80, v80 row_half_mirror row_mask:0xf bank_mask:0xf bound_ctrl:1
	s_nop 1
	v_add_f32_dpp v80, v80, v80 row_mirror row_mask:0xf bank_mask:0xf bound_ctrl:1
	v_pk_fma_f32 v[52:53], v[64:65], v[80:81], v[78:79] op_sel_hi:[1,0,1] neg_lo:[0,1,0] neg_hi:[0,1,0]
	v_pk_fma_f32 v[50:51], v[62:63], v[80:81], v[76:77] op_sel_hi:[1,0,1] neg_lo:[0,1,0] neg_hi:[0,1,0]
	v_pk_mul_f32 v[82:83], v[72:73], v[52:53]
	s_nop 0
	v_pk_fma_f32 v[82:83], v[70:71], v[50:51], v[82:83]
	s_nop 0
	v_add_f32_e32 v82, v82, v83
	ds_write_b32 v244, v82 offset:3584
	s_waitcnt lgkmcnt(2)
	v_pk_mul_f32 v[80:81], v[52:53], v[8:9]
	v_pk_mul_f32 v[76:77], v[14:15], v[22:23] op_sel_hi:[1,0]
	v_pk_fma_f32 v[80:81], v[50:51], v[6:7], v[80:81]
	v_pk_mul_f32 v[78:79], v[16:17], v[22:23] op_sel_hi:[1,0]
	v_add_f32_e32 v80, v80, v81
	v_pk_fma_f32 v[76:77], v[50:51], v[2:3], v[76:77]
	v_pk_fma_f32 v[78:79], v[52:53], v[4:5], v[78:79]
	v_add_f32_dpp v80, v80, v80 quad_perm:[1,0,3,2] row_mask:0xf bank_mask:0xf bound_ctrl:1
	s_nop 1
	v_add_f32_dpp v80, v80, v80 quad_perm:[2,3,0,1] row_mask:0xf bank_mask:0xf bound_ctrl:1
	s_nop 1
	v_add_f32_dpp v80, v80, v80 row_half_mirror row_mask:0xf bank_mask:0xf bound_ctrl:1
	s_nop 1
	v_add_f32_dpp v80, v80, v80 row_mirror row_mask:0xf bank_mask:0xf bound_ctrl:1
	v_pk_fma_f32 v[52:53], v[12:13], v[80:81], v[78:79] op_sel_hi:[1,0,1] neg_lo:[0,1,0] neg_hi:[0,1,0]
	v_pk_fma_f32 v[50:51], v[10:11], v[80:81], v[76:77] op_sel_hi:[1,0,1] neg_lo:[0,1,0] neg_hi:[0,1,0]
	v_pk_mul_f32 v[82:83], v[20:21], v[52:53]
	s_nop 0
	v_pk_fma_f32 v[82:83], v[18:19], v[50:51], v[82:83]
	s_nop 0
	v_add_f32_e32 v82, v82, v83
	ds_write_b32 v244, v82 offset:3840

.LBB0_202:
	s_or_b64 exec, exec, s[20:21]
	s_or_b32 s28, s79, 1
	s_waitcnt lgkmcnt(0)
	s_barrier
	s_and_saveexec_b64 s[20:21], s[40:41]
	s_cbranch_execz .LBB0_211
	ds_read_b128 v[2:5], v228 offset:20480
	ds_read_b128 v[6:9], v228 offset:24576
	ds_read_b128 v[10:13], v228 offset:28672
	ds_read_b128 v[14:17], v228 offset:32768
	ds_read_b128 v[18:21], v228 offset:36864
	ds_read_b32 v22, v229 offset:41984
	ds_read_b128 v[24:27], v228 offset:20736
	ds_read_b128 v[28:31], v228 offset:24832
	ds_read_b128 v[32:35], v228 offset:28928
	ds_read_b128 v[36:39], v228 offset:33024
	ds_read_b128 v[40:43], v228 offset:37120
	ds_read_b32 v44, v229 offset:42048
	s_waitcnt vmcnt(0)
	s_waitcnt lgkmcnt(6)
	v_pk_mul_f32 v[80:81], v[52:53], v[8:9]
	v_pk_mul_f32 v[76:77], v[14:15], v[22:23] op_sel_hi:[1,0]
	v_pk_fma_f32 v[80:81], v[50:51], v[6:7], v[80:81]
	v_pk_mul_f32 v[78:79], v[16:17], v[22:23] op_sel_hi:[1,0]
	v_add_f32_e32 v80, v80, v81
	v_pk_fma_f32 v[76:77], v[50:51], v[2:3], v[76:77]
	v_pk_fma_f32 v[78:79], v[52:53], v[4:5], v[78:79]
	v_add_f32_dpp v80, v80, v80 quad_perm:[1,0,3,2] row_mask:0xf bank_mask:0xf bound_ctrl:1
	ds_read_b128 v[54:57], v228 offset:20992
	ds_read_b128 v[58:61], v228 offset:25088
	v_add_f32_dpp v80, v80, v80 quad_perm:[2,3,0,1] row_mask:0xf bank_mask:0xf bound_ctrl:1
	ds_read_b128 v[62:65], v228 offset:29184
	ds_read_b128 v[66:69], v228 offset:33280
	v_add_f32_dpp v80, v80, v80 row_half_mirror row_mask:0xf bank_mask:0xf bound_ctrl:1
	ds_read_b128 v[70:73], v228 offset:37376
	ds_read_b32 v74, v229 offset:42112
	v_add_f32_dpp v80, v80, v80 row_mirror row_mask:0xf bank_mask:0xf bound_ctrl:1
	v_pk_fma_f32 v[52:53], v[12:13], v[80:81], v[78:79] op_sel_hi:[1,0,1] neg_lo:[0,1,0] neg_hi:[0,1,0]
	v_pk_fma_f32 v[50:51], v[10:11], v[80:81], v[76:77] op_sel_hi:[1,0,1] neg_lo:[0,1,0] neg_hi:[0,1,0]
	v_pk_mul_f32 v[82:83], v[20:21], v[52:53]
	s_nop 0
	v_pk_fma_f32 v[82:83], v[18:19], v[50:51], v[82:83]
	s_nop 0
	v_add_f32_e32 v82, v82, v83
	ds_write_b32 v246, v82
	s_waitcnt lgkmcnt(7)
	v_pk_mul_f32 v[80:81], v[52:53], v[30:31]
	v_pk_mul_f32 v[76:77], v[36:37], v[44:45] op_sel_hi:[1,0]
	v_pk_fma_f32 v[80:81], v[50:51], v[28:29], v[80:81]
	v_pk_mul_f32 v[78:79], v[38:39], v[44:45] op_sel_hi:[1,0]
	v_add_f32_e32 v80, v80, v81
	v_pk_fma_f32 v[76:77], v[50:51], v[24:25], v[76:77]
	v_pk_fma_f32 v[78:79], v[52:53], v[26:27], v[78:79]
	v_add_f32_dpp v80, v80, v80 quad_perm:[1,0,3,2] row_mask:0xf bank_mask:0xf bound_ctrl:1
	ds_read_b128 v[2:5], v228 offset:21248
	ds_read_b128 v[6:9], v228 offset:25344
	v_add_f32_dpp v80, v80, v80 quad_perm:[2,3,0,1] row_mask:0xf bank_mask:0xf bound_ctrl:1
	ds_read_b128 v[10:13], v228 offset:29440
	ds_read_b128 v[14:17], v228 offset:33536
	v_add_f32_dpp v80, v80, v80 row_half_mirror row_mask:0xf bank_mask:0xf bound_ctrl:1
	ds_read_b128 v[18:21], v228 offset:37632
	ds_read_b32 v22, v229 offset:42176
	v_add_f32_dpp v80, v80, v80 row_mirror row_mask:0xf bank_mask:0xf bound_ctrl:1
	v_pk_fma_f32 v[52:53], v[34:35], v[80:81], v[78:79] op_sel_hi:[1,0,1] neg_lo:[0,1,0] neg_hi:[0,1,0]
	v_pk_fma_f32 v[50:51], v[32:33], v[80:81], v[76:77] op_sel_hi:[1,0,1] neg_lo:[0,1,0] neg_hi:[0,1,0]
	v_pk_mul_f32 v[82:83], v[42:43], v[52:53]
	s_nop 0
	v_pk_fma_f32 v[82:83], v[40:41], v[50:51], v[82:83]
	s_nop 0
	v_add_f32_e32 v82, v82, v83
	ds_write_b32 v246, v82 offset:256
	s_waitcnt lgkmcnt(8)
	v_pk_mul_f32 v[80:81], v[52:53], v[60:61]
	v_pk_mul_f32 v[76:77], v[66:67], v[74:75] op_sel_hi:[1,0]
	v_pk_fma_f32 v[80:81], v[50:51], v[58:59], v[80:81]
	v_pk_mul_f32 v[78:79], v[68:69], v[74:75] op_sel_hi:[1,0]
	v_add_f32_e32 v80, v80, v81
	v_pk_fma_f32 v[76:77], v[50:51], v[54:55], v[76:77]
	v_pk_fma_f32 v[78:79], v[52:53], v[56:57], v[78:79]
	v_add_f32_dpp v80, v80, v80 quad_perm:[1,0,3,2] row_mask:0xf bank_mask:0xf bound_ctrl:1
	ds_read_b128 v[24:27], v228 offset:21504
	ds_read_b128 v[28:31], v228 offset:25600
	v_add_f32_dpp v80, v80, v80 quad_perm:[2,3,0,1] row_mask:0xf bank_mask:0xf bound_ctrl:1
	ds_read_b128 v[32:35], v228 offset:29696
	ds_read_b128 v[36:39], v228 offset:33792
	v_add_f32_dpp v80, v80, v80 row_half_mirror row_mask:0xf bank_mask:0xf bound_ctrl:1
	ds_read_b128 v[40:43], v228 offset:37888
	ds_read_b32 v44, v229 offset:42240
	v_add_f32_dpp v80, v80, v80 row_mirror row_mask:0xf bank_mask:0xf bound_ctrl:1
	v_pk_fma_f32 v[52:53], v[64:65], v[80:81], v[78:79] op_sel_hi:[1,0,1] neg_lo:[0,1,0] neg_hi:[0,1,0]
	v_pk_fma_f32 v[50:51], v[62:63], v[80:81], v[76:77] op_sel_hi:[1,0,1] neg_lo:[0,1,0] neg_hi:[0,1,0]
	v_pk_mul_f32 v[82:83], v[72:73], v[52:53]
	s_nop 0
	v_pk_fma_f32 v[82:83], v[70:71], v[50:51], v[82:83]
	s_nop 0
	v_add_f32_e32 v82, v82, v83
	ds_write_b32 v246, v82 offset:512
	s_waitcnt lgkmcnt(8)
	v_pk_mul_f32 v[80:81], v[52:53], v[8:9]
	v_pk_mul_f32 v[76:77], v[14:15], v[22:23] op_sel_hi:[1,0]
	v_pk_fma_f32 v[80:81], v[50:51], v[6:7], v[80:81]
	v_pk_mul_f32 v[78:79], v[16:17], v[22:23] op_sel_hi:[1,0]
	v_add_f32_e32 v80, v80, v81
	v_pk_fma_f32 v[76:77], v[50:51], v[2:3], v[76:77]
	v_pk_fma_f32 v[78:79], v[52:53], v[4:5], v[78:79]
	v_add_f32_dpp v80, v80, v80 quad_perm:[1,0,3,2] row_mask:0xf bank_mask:0xf bound_ctrl:1
	ds_read_b128 v[54:57], v228 offset:21760
	ds_read_b128 v[58:61], v228 offset:25856
	v_add_f32_dpp v80, v80, v80 quad_perm:[2,3,0,1] row_mask:0xf bank_mask:0xf bound_ctrl:1
	ds_read_b128 v[62:65], v228 offset:29952
	ds_read_b128 v[66:69], v228 offset:34048
	v_add_f32_dpp v80, v80, v80 row_half_mirror row_mask:0xf bank_mask:0xf bound_ctrl:1
	ds_read_b128 v[70:73], v228 offset:38144
	ds_read_b32 v74, v229 offset:42304
	v_add_f32_dpp v80, v80, v80 row_mirror row_mask:0xf bank_mask:0xf bound_ctrl:1
	v_pk_fma_f32 v[52:53], v[12:13], v[80:81], v[78:79] op_sel_hi:[1,0,1] neg_lo:[0,1,0] neg_hi:[0,1,0]
	v_pk_fma_f32 v[50:51], v[10:11], v[80:81], v[76:77] op_sel_hi:[1,0,1] neg_lo:[0,1,0] neg_hi:[0,1,0]
	v_pk_mul_f32 v[82:83], v[20:21], v[52:53]
	s_nop 0
	v_pk_fma_f32 v[82:83], v[18:19], v[50:51], v[82:83]
	s_nop 0
	v_add_f32_e32 v82, v82, v83
	ds_write_b32 v246, v82 offset:768
	s_waitcnt lgkmcnt(8)
	v_pk_mul_f32 v[80:81], v[52:53], v[30:31]
	v_pk_mul_f32 v[76:77], v[36:37], v[44:45] op_sel_hi:[1,0]
	v_pk_fma_f32 v[80:81], v[50:51], v[28:29], v[80:81]
	v_pk_mul_f32 v[78:79], v[38:39], v[44:45] op_sel_hi:[1,0]
	v_add_f32_e32 v80, v80, v81
	v_pk_fma_f32 v[76:77], v[50:51], v[24:25], v[76:77]
	v_pk_fma_f32 v[78:79], v[52:53], v[26:27], v[78:79]
	v_add_f32_dpp v80, v80, v80 quad_perm:[1,0,3,2] row_mask:0xf bank_mask:0xf bound_ctrl:1
	ds_read_b128 v[2:5], v228 offset:22016
	ds_read_b128 v[6:9], v228 offset:26112
	v_add_f32_dpp v80, v80, v80 quad_perm:[2,3,0,1] row_mask:0xf bank_mask:0xf bound_ctrl:1
	ds_read_b128 v[10:13], v228 offset:30208
	ds_read_b128 v[14:17], v228 offset:34304
	v_add_f32_dpp v80, v80, v80 row_half_mirror row_mask:0xf bank_mask:0xf bound_ctrl:1
	ds_read_b128 v[18:21], v228 offset:38400
	ds_read_b32 v22, v229 offset:42368
	v_add_f32_dpp v80, v80, v80 row_mirror row_mask:0xf bank_mask:0xf bound_ctrl:1
	v_pk_fma_f32 v[52:53], v[34:35], v[80:81], v[78:79] op_sel_hi:[1,0,1] neg_lo:[0,1,0] neg_hi:[0,1,0]
	v_pk_fma_f32 v[50:51], v[32:33], v[80:81], v[76:77] op_sel_hi:[1,0,1] neg_lo:[0,1,0] neg_hi:[0,1,0]
	v_pk_mul_f32 v[82:83], v[42:43], v[52:53]
	s_nop 0
	v_pk_fma_f32 v[82:83], v[40:41], v[50:51], v[82:83]
	s_nop 0
	v_add_f32_e32 v82, v82, v83
	ds_write_b32 v246, v82 offset:1024
	s_waitcnt lgkmcnt(8)
	v_pk_mul_f32 v[80:81], v[52:53], v[60:61]
	v_pk_mul_f32 v[76:77], v[66:67], v[74:75] op_sel_hi:[1,0]
	v_pk_fma_f32 v[80:81], v[50:51], v[58:59], v[80:81]
	v_pk_mul_f32 v[78:79], v[68:69], v[74:75] op_sel_hi:[1,0]
	v_add_f32_e32 v80, v80, v81
	v_pk_fma_f32 v[76:77], v[50:51], v[54:55], v[76:77]
	v_pk_fma_f32 v[78:79], v[52:53], v[56:57], v[78:79]
	v_add_f32_dpp v80, v80, v80 quad_perm:[1,0,3,2] row_mask:0xf bank_mask:0xf bound_ctrl:1
	ds_read_b128 v[24:27], v228 offset:22272
	ds_read_b128 v[28:31], v228 offset:26368
	v_add_f32_dpp v80, v80, v80 quad_perm:[2,3,0,1] row_mask:0xf bank_mask:0xf bound_ctrl:1
	ds_read_b128 v[32:35], v228 offset:30464
	ds_read_b128 v[36:39], v228 offset:34560
	v_add_f32_dpp v80, v80, v80 row_half_mirror row_mask:0xf bank_mask:0xf bound_ctrl:1
	ds_read_b128 v[40:43], v228 offset:38656
	ds_read_b32 v44, v229 offset:42432
	v_add_f32_dpp v80, v80, v80 row_mirror row_mask:0xf bank_mask:0xf bound_ctrl:1
	v_pk_fma_f32 v[52:53], v[64:65], v[80:81], v[78:79] op_sel_hi:[1,0,1] neg_lo:[0,1,0] neg_hi:[0,1,0]
	v_pk_fma_f32 v[50:51], v[62:63], v[80:81], v[76:77] op_sel_hi:[1,0,1] neg_lo:[0,1,0] neg_hi:[0,1,0]
	v_pk_mul_f32 v[82:83], v[72:73], v[52:53]
	s_nop 0
	v_pk_fma_f32 v[82:83], v[70:71], v[50:51], v[82:83]
	s_nop 0
	v_add_f32_e32 v82, v82, v83
	ds_write_b32 v246, v82 offset:1280
	s_waitcnt lgkmcnt(8)
	v_pk_mul_f32 v[80:81], v[52:53], v[8:9]
	v_pk_mul_f32 v[76:77], v[14:15], v[22:23] op_sel_hi:[1,0]
	v_pk_fma_f32 v[80:81], v[50:51], v[6:7], v[80:81]
	v_pk_mul_f32 v[78:79], v[16:17], v[22:23] op_sel_hi:[1,0]
	v_add_f32_e32 v80, v80, v81
	v_pk_fma_f32 v[76:77], v[50:51], v[2:3], v[76:77]
	v_pk_fma_f32 v[78:79], v[52:53], v[4:5], v[78:79]
	v_add_f32_dpp v80, v80, v80 quad_perm:[1,0,3,2] row_mask:0xf bank_mask:0xf bound_ctrl:1
	ds_read_b128 v[54:57], v228 offset:22528
	ds_read_b128 v[58:61], v228 offset:26624
	v_add_f32_dpp v80, v80, v80 quad_perm:[2,3,0,1] row_mask:0xf bank_mask:0xf bound_ctrl:1
	ds_read_b128 v[62:65], v228 offset:30720
	ds_read_b128 v[66:69], v228 offset:34816
	v_add_f32_dpp v80, v80, v80 row_half_mirror row_mask:0xf bank_mask:0xf bound_ctrl:1
	ds_read_b128 v[70:73], v228 offset:38912
	ds_read_b32 v74, v229 offset:42496
	v_add_f32_dpp v80, v80, v80 row_mirror row_mask:0xf bank_mask:0xf bound_ctrl:1
	v_pk_fma_f32 v[52:53], v[12:13], v[80:81], v[78:79] op_sel_hi:[1,0,1] neg_lo:[0,1,0] neg_hi:[0,1,0]
	v_pk_fma_f32 v[50:51], v[10:11], v[80:81], v[76:77] op_sel_hi:[1,0,1] neg_lo:[0,1,0] neg_hi:[0,1,0]
	v_pk_mul_f32 v[82:83], v[20:21], v[52:53]
	s_nop 0
	v_pk_fma_f32 v[82:83], v[18:19], v[50:51], v[82:83]
	s_nop 0
	v_add_f32_e32 v82, v82, v83
	ds_write_b32 v246, v82 offset:1536
	s_waitcnt lgkmcnt(8)
	v_pk_mul_f32 v[80:81], v[52:53], v[30:31]
	v_pk_mul_f32 v[76:77], v[36:37], v[44:45] op_sel_hi:[1,0]
	v_pk_fma_f32 v[80:81], v[50:51], v[28:29], v[80:81]
	v_pk_mul_f32 v[78:79], v[38:39], v[44:45] op_sel_hi:[1,0]
	v_add_f32_e32 v80, v80, v81
	v_pk_fma_f32 v[76:77], v[50:51], v[24:25], v[76:77]
	v_pk_fma_f32 v[78:79], v[52:53], v[26:27], v[78:79]
	v_add_f32_dpp v80, v80, v80 quad_perm:[1,0,3,2] row_mask:0xf bank_mask:0xf bound_ctrl:1
	ds_read_b128 v[2:5], v228 offset:22784
	ds_read_b128 v[6:9], v228 offset:26880
	v_add_f32_dpp v80, v80, v80 quad_perm:[2,3,0,1] row_mask:0xf bank_mask:0xf bound_ctrl:1
	ds_read_b128 v[10:13], v228 offset:30976
	ds_read_b128 v[14:17], v228 offset:35072
	v_add_f32_dpp v80, v80, v80 row_half_mirror row_mask:0xf bank_mask:0xf bound_ctrl:1
	ds_read_b128 v[18:21], v228 offset:39168
	ds_read_b32 v22, v229 offset:42560
	v_add_f32_dpp v80, v80, v80 row_mirror row_mask:0xf bank_mask:0xf bound_ctrl:1
	v_pk_fma_f32 v[52:53], v[34:35], v[80:81], v[78:79] op_sel_hi:[1,0,1] neg_lo:[0,1,0] neg_hi:[0,1,0]
	v_pk_fma_f32 v[50:51], v[32:33], v[80:81], v[76:77] op_sel_hi:[1,0,1] neg_lo:[0,1,0] neg_hi:[0,1,0]
	v_pk_mul_f32 v[82:83], v[42:43], v[52:53]
	s_nop 0
	v_pk_fma_f32 v[82:83], v[40:41], v[50:51], v[82:83]
	s_nop 0
	v_add_f32_e32 v82, v82, v83
	ds_write_b32 v246, v82 offset:1792
	s_waitcnt lgkmcnt(8)
	v_pk_mul_f32 v[80:81], v[52:53], v[60:61]
	v_pk_mul_f32 v[76:77], v[66:67], v[74:75] op_sel_hi:[1,0]
	v_pk_fma_f32 v[80:81], v[50:51], v[58:59], v[80:81]
	v_pk_mul_f32 v[78:79], v[68:69], v[74:75] op_sel_hi:[1,0]
	v_add_f32_e32 v80, v80, v81
	v_pk_fma_f32 v[76:77], v[50:51], v[54:55], v[76:77]
	v_pk_fma_f32 v[78:79], v[52:53], v[56:57], v[78:79]
	v_add_f32_dpp v80, v80, v80 quad_perm:[1,0,3,2] row_mask:0xf bank_mask:0xf bound_ctrl:1
	ds_read_b128 v[24:27], v228 offset:23040
	ds_read_b128 v[28:31], v228 offset:27136
	v_add_f32_dpp v80, v80, v80 quad_perm:[2,3,0,1] row_mask:0xf bank_mask:0xf bound_ctrl:1
	ds_read_b128 v[32:35], v228 offset:31232
	ds_read_b128 v[36:39], v228 offset:35328
	v_add_f32_dpp v80, v80, v80 row_half_mirror row_mask:0xf bank_mask:0xf bound_ctrl:1
	ds_read_b128 v[40:43], v228 offset:39424
	ds_read_b32 v44, v229 offset:42624
	v_add_f32_dpp v80, v80, v80 row_mirror row_mask:0xf bank_mask:0xf bound_ctrl:1
	v_pk_fma_f32 v[52:53], v[64:65], v[80:81], v[78:79] op_sel_hi:[1,0,1] neg_lo:[0,1,0] neg_hi:[0,1,0]
	v_pk_fma_f32 v[50:51], v[62:63], v[80:81], v[76:77] op_sel_hi:[1,0,1] neg_lo:[0,1,0] neg_hi:[0,1,0]
	v_pk_mul_f32 v[82:83], v[72:73], v[52:53]
	s_nop 0
	v_pk_fma_f32 v[82:83], v[70:71], v[50:51], v[82:83]
	s_nop 0
	v_add_f32_e32 v82, v82, v83
	ds_write_b32 v246, v82 offset:2048
	s_waitcnt lgkmcnt(8)
	v_pk_mul_f32 v[80:81], v[52:53], v[8:9]
	v_pk_mul_f32 v[76:77], v[14:15], v[22:23] op_sel_hi:[1,0]
	v_pk_fma_f32 v[80:81], v[50:51], v[6:7], v[80:81]
	v_pk_mul_f32 v[78:79], v[16:17], v[22:23] op_sel_hi:[1,0]
	v_add_f32_e32 v80, v80, v81
	v_pk_fma_f32 v[76:77], v[50:51], v[2:3], v[76:77]
	v_pk_fma_f32 v[78:79], v[52:53], v[4:5], v[78:79]
	v_add_f32_dpp v80, v80, v80 quad_perm:[1,0,3,2] row_mask:0xf bank_mask:0xf bound_ctrl:1
	ds_read_b128 v[54:57], v228 offset:23296
	ds_read_b128 v[58:61], v228 offset:27392
	v_add_f32_dpp v80, v80, v80 quad_perm:[2,3,0,1] row_mask:0xf bank_mask:0xf bound_ctrl:1
	ds_read_b128 v[62:65], v228 offset:31488
	ds_read_b128 v[66:69], v228 offset:35584
	v_add_f32_dpp v80, v80, v80 row_half_mirror row_mask:0xf bank_mask:0xf bound_ctrl:1
	ds_read_b128 v[70:73], v228 offset:39680
	ds_read_b32 v74, v229 offset:42688
	v_add_f32_dpp v80, v80, v80 row_mirror row_mask:0xf bank_mask:0xf bound_ctrl:1
	v_pk_fma_f32 v[52:53], v[12:13], v[80:81], v[78:79] op_sel_hi:[1,0,1] neg_lo:[0,1,0] neg_hi:[0,1,0]
	v_pk_fma_f32 v[50:51], v[10:11], v[80:81], v[76:77] op_sel_hi:[1,0,1] neg_lo:[0,1,0] neg_hi:[0,1,0]
	v_pk_mul_f32 v[82:83], v[20:21], v[52:53]
	s_nop 0
	v_pk_fma_f32 v[82:83], v[18:19], v[50:51], v[82:83]
	s_nop 0
	v_add_f32_e32 v82, v82, v83
	ds_write_b32 v246, v82 offset:2304
	s_waitcnt lgkmcnt(8)
	v_pk_mul_f32 v[80:81], v[52:53], v[30:31]
	v_pk_mul_f32 v[76:77], v[36:37], v[44:45] op_sel_hi:[1,0]
	v_pk_fma_f32 v[80:81], v[50:51], v[28:29], v[80:81]
	v_pk_mul_f32 v[78:79], v[38:39], v[44:45] op_sel_hi:[1,0]
	v_add_f32_e32 v80, v80, v81
	v_pk_fma_f32 v[76:77], v[50:51], v[24:25], v[76:77]
	v_pk_fma_f32 v[78:79], v[52:53], v[26:27], v[78:79]
	v_add_f32_dpp v80, v80, v80 quad_perm:[1,0,3,2] row_mask:0xf bank_mask:0xf bound_ctrl:1
	ds_read_b128 v[2:5], v228 offset:23552
	ds_read_b128 v[6:9], v228 offset:27648
	v_add_f32_dpp v80, v80, v80 quad_perm:[2,3,0,1] row_mask:0xf bank_mask:0xf bound_ctrl:1
	ds_read_b128 v[10:13], v228 offset:31744
	ds_read_b128 v[14:17], v228 offset:35840
	v_add_f32_dpp v80, v80, v80 row_half_mirror row_mask:0xf bank_mask:0xf bound_ctrl:1
	ds_read_b128 v[18:21], v228 offset:39936
	ds_read_b32 v22, v229 offset:42752
	v_add_f32_dpp v80, v80, v80 row_mirror row_mask:0xf bank_mask:0xf bound_ctrl:1
	v_pk_fma_f32 v[52:53], v[34:35], v[80:81], v[78:79] op_sel_hi:[1,0,1] neg_lo:[0,1,0] neg_hi:[0,1,0]
	v_pk_fma_f32 v[50:51], v[32:33], v[80:81], v[76:77] op_sel_hi:[1,0,1] neg_lo:[0,1,0] neg_hi:[0,1,0]
	v_pk_mul_f32 v[82:83], v[42:43], v[52:53]
	s_nop 0
	v_pk_fma_f32 v[82:83], v[40:41], v[50:51], v[82:83]
	s_nop 0
	v_add_f32_e32 v82, v82, v83
	ds_write_b32 v246, v82 offset:2560
	s_waitcnt lgkmcnt(8)
	v_pk_mul_f32 v[80:81], v[52:53], v[60:61]
	v_pk_mul_f32 v[76:77], v[66:67], v[74:75] op_sel_hi:[1,0]
	v_pk_fma_f32 v[80:81], v[50:51], v[58:59], v[80:81]
	v_pk_mul_f32 v[78:79], v[68:69], v[74:75] op_sel_hi:[1,0]
	v_add_f32_e32 v80, v80, v81
	v_pk_fma_f32 v[76:77], v[50:51], v[54:55], v[76:77]
	v_pk_fma_f32 v[78:79], v[52:53], v[56:57], v[78:79]
	v_add_f32_dpp v80, v80, v80 quad_perm:[1,0,3,2] row_mask:0xf bank_mask:0xf bound_ctrl:1
	ds_read_b128 v[24:27], v228 offset:23808
	ds_read_b128 v[28:31], v228 offset:27904
	v_add_f32_dpp v80, v80, v80 quad_perm:[2,3,0,1] row_mask:0xf bank_mask:0xf bound_ctrl:1
	ds_read_b128 v[32:35], v228 offset:32000
	ds_read_b128 v[36:39], v228 offset:36096
	v_add_f32_dpp v80, v80, v80 row_half_mirror row_mask:0xf bank_mask:0xf bound_ctrl:1
	ds_read_b128 v[40:43], v228 offset:40192
	ds_read_b32 v44, v229 offset:42816
	v_add_f32_dpp v80, v80, v80 row_mirror row_mask:0xf bank_mask:0xf bound_ctrl:1
	v_pk_fma_f32 v[52:53], v[64:65], v[80:81], v[78:79] op_sel_hi:[1,0,1] neg_lo:[0,1,0] neg_hi:[0,1,0]
	v_pk_fma_f32 v[50:51], v[62:63], v[80:81], v[76:77] op_sel_hi:[1,0,1] neg_lo:[0,1,0] neg_hi:[0,1,0]
	v_pk_mul_f32 v[82:83], v[72:73], v[52:53]
	s_nop 0
	v_pk_fma_f32 v[82:83], v[70:71], v[50:51], v[82:83]
	s_nop 0
	v_add_f32_e32 v82, v82, v83
	ds_write_b32 v246, v82 offset:2816
	s_waitcnt lgkmcnt(8)
	v_pk_mul_f32 v[80:81], v[52:53], v[8:9]
	v_pk_mul_f32 v[76:77], v[14:15], v[22:23] op_sel_hi:[1,0]
	v_pk_fma_f32 v[80:81], v[50:51], v[6:7], v[80:81]
	v_pk_mul_f32 v[78:79], v[16:17], v[22:23] op_sel_hi:[1,0]
	v_add_f32_e32 v80, v80, v81
	v_pk_fma_f32 v[76:77], v[50:51], v[2:3], v[76:77]
	v_pk_fma_f32 v[78:79], v[52:53], v[4:5], v[78:79]
	v_add_f32_dpp v80, v80, v80 quad_perm:[1,0,3,2] row_mask:0xf bank_mask:0xf bound_ctrl:1
	ds_read_b128 v[54:57], v228 offset:24064
	ds_read_b128 v[58:61], v228 offset:28160
	v_add_f32_dpp v80, v80, v80 quad_perm:[2,3,0,1] row_mask:0xf bank_mask:0xf bound_ctrl:1
	ds_read_b128 v[62:65], v228 offset:32256
	ds_read_b128 v[66:69], v228 offset:36352
	v_add_f32_dpp v80, v80, v80 row_half_mirror row_mask:0xf bank_mask:0xf bound_ctrl:1
	ds_read_b128 v[70:73], v228 offset:40448
	ds_read_b32 v74, v229 offset:42880
	v_add_f32_dpp v80, v80, v80 row_mirror row_mask:0xf bank_mask:0xf bound_ctrl:1
	v_pk_fma_f32 v[52:53], v[12:13], v[80:81], v[78:79] op_sel_hi:[1,0,1] neg_lo:[0,1,0] neg_hi:[0,1,0]
	v_pk_fma_f32 v[50:51], v[10:11], v[80:81], v[76:77] op_sel_hi:[1,0,1] neg_lo:[0,1,0] neg_hi:[0,1,0]
	v_pk_mul_f32 v[82:83], v[20:21], v[52:53]
	s_nop 0
	v_pk_fma_f32 v[82:83], v[18:19], v[50:51], v[82:83]
	s_nop 0
	v_add_f32_e32 v82, v82, v83
	ds_write_b32 v246, v82 offset:3072
	s_waitcnt lgkmcnt(8)
	v_pk_mul_f32 v[80:81], v[52:53], v[30:31]
	v_pk_mul_f32 v[76:77], v[36:37], v[44:45] op_sel_hi:[1,0]
	v_pk_fma_f32 v[80:81], v[50:51], v[28:29], v[80:81]
	v_pk_mul_f32 v[78:79], v[38:39], v[44:45] op_sel_hi:[1,0]
	v_add_f32_e32 v80, v80, v81
	v_pk_fma_f32 v[76:77], v[50:51], v[24:25], v[76:77]
	v_pk_fma_f32 v[78:79], v[52:53], v[26:27], v[78:79]
	v_add_f32_dpp v80, v80, v80 quad_perm:[1,0,3,2] row_mask:0xf bank_mask:0xf bound_ctrl:1
	ds_read_b128 v[2:5], v228 offset:24320
	ds_read_b128 v[6:9], v228 offset:28416
	v_add_f32_dpp v80, v80, v80 quad_perm:[2,3,0,1] row_mask:0xf bank_mask:0xf bound_ctrl:1
	ds_read_b128 v[10:13], v228 offset:32512
	ds_read_b128 v[14:17], v228 offset:36608
	v_add_f32_dpp v80, v80, v80 row_half_mirror row_mask:0xf bank_mask:0xf bound_ctrl:1
	ds_read_b128 v[18:21], v228 offset:40704
	ds_read_b32 v22, v229 offset:42944
	v_add_f32_dpp v80, v80, v80 row_mirror row_mask:0xf bank_mask:0xf bound_ctrl:1
	v_pk_fma_f32 v[52:53], v[34:35], v[80:81], v[78:79] op_sel_hi:[1,0,1] neg_lo:[0,1,0] neg_hi:[0,1,0]
	v_pk_fma_f32 v[50:51], v[32:33], v[80:81], v[76:77] op_sel_hi:[1,0,1] neg_lo:[0,1,0] neg_hi:[0,1,0]
	v_pk_mul_f32 v[82:83], v[42:43], v[52:53]
	s_nop 0
	v_pk_fma_f32 v[82:83], v[40:41], v[50:51], v[82:83]
	s_nop 0
	v_add_f32_e32 v82, v82, v83
	ds_write_b32 v246, v82 offset:3328
	s_waitcnt lgkmcnt(8)
	v_pk_mul_f32 v[80:81], v[52:53], v[60:61]
	v_pk_mul_f32 v[76:77], v[66:67], v[74:75] op_sel_hi:[1,0]
	v_pk_fma_f32 v[80:81], v[50:51], v[58:59], v[80:81]
	v_pk_mul_f32 v[78:79], v[68:69], v[74:75] op_sel_hi:[1,0]
	v_add_f32_e32 v80, v80, v81
	v_pk_fma_f32 v[76:77], v[50:51], v[54:55], v[76:77]
	v_pk_fma_f32 v[78:79], v[52:53], v[56:57], v[78:79]
	v_add_f32_dpp v80, v80, v80 quad_perm:[1,0,3,2] row_mask:0xf bank_mask:0xf bound_ctrl:1
	s_nop 1
	v_add_f32_dpp v80, v80, v80 quad_perm:[2,3,0,1] row_mask:0xf bank_mask:0xf bound_ctrl:1
	s_nop 1
	v_add_f32_dpp v80, v80, v80 row_half_mirror row_mask:0xf bank_mask:0xf bound_ctrl:1
	s_nop 1
	v_add_f32_dpp v80, v80, v80 row_mirror row_mask:0xf bank_mask:0xf bound_ctrl:1
	v_pk_fma_f32 v[52:53], v[64:65], v[80:81], v[78:79] op_sel_hi:[1,0,1] neg_lo:[0,1,0] neg_hi:[0,1,0]
	v_pk_fma_f32 v[50:51], v[62:63], v[80:81], v[76:77] op_sel_hi:[1,0,1] neg_lo:[0,1,0] neg_hi:[0,1,0]
	v_pk_mul_f32 v[82:83], v[72:73], v[52:53]
	s_nop 0
	v_pk_fma_f32 v[82:83], v[70:71], v[50:51], v[82:83]
	s_nop 0
	v_add_f32_e32 v82, v82, v83
	ds_write_b32 v246, v82 offset:3584
	s_waitcnt lgkmcnt(2)
	v_pk_mul_f32 v[80:81], v[52:53], v[8:9]
	v_pk_mul_f32 v[76:77], v[14:15], v[22:23] op_sel_hi:[1,0]
	v_pk_fma_f32 v[80:81], v[50:51], v[6:7], v[80:81]
	v_pk_mul_f32 v[78:79], v[16:17], v[22:23] op_sel_hi:[1,0]
	v_add_f32_e32 v80, v80, v81
	v_pk_fma_f32 v[76:77], v[50:51], v[2:3], v[76:77]
	v_pk_fma_f32 v[78:79], v[52:53], v[4:5], v[78:79]
	v_add_f32_dpp v80, v80, v80 quad_perm:[1,0,3,2] row_mask:0xf bank_mask:0xf bound_ctrl:1
	s_nop 1
	v_add_f32_dpp v80, v80, v80 quad_perm:[2,3,0,1] row_mask:0xf bank_mask:0xf bound_ctrl:1
	s_nop 1
	v_add_f32_dpp v80, v80, v80 row_half_mirror row_mask:0xf bank_mask:0xf bound_ctrl:1
	s_nop 1
	v_add_f32_dpp v80, v80, v80 row_mirror row_mask:0xf bank_mask:0xf bound_ctrl:1
	v_pk_fma_f32 v[52:53], v[12:13], v[80:81], v[78:79] op_sel_hi:[1,0,1] neg_lo:[0,1,0] neg_hi:[0,1,0]
	v_pk_fma_f32 v[50:51], v[10:11], v[80:81], v[76:77] op_sel_hi:[1,0,1] neg_lo:[0,1,0] neg_hi:[0,1,0]
	v_pk_mul_f32 v[82:83], v[20:21], v[52:53]
	s_nop 0
	v_pk_fma_f32 v[82:83], v[18:19], v[50:51], v[82:83]
	s_nop 0
	v_add_f32_e32 v82, v82, v83
	ds_write_b32 v246, v82 offset:3840

.LBB0_481:
	v_readlane_b32 s4, v251, 14
	v_readlane_b32 s5, v251, 15
	s_movk_i32 s28, 0x400
	s_mov_b64 s[20:21], 0x400
	v_readlane_b32 s6, v251, 16
	v_readlane_b32 s7, v251, 17
	v_readlane_b32 s8, v251, 18
	v_readlane_b32 s9, v251, 19
	v_readlane_b32 s10, v251, 20
	v_readlane_b32 s11, v251, 21
	v_readlane_b32 s12, v251, 22
	v_readlane_b32 s13, v251, 23
	v_readlane_b32 s14, v251, 24
	v_readlane_b32 s15, v251, 25
	v_readlane_b32 s16, v251, 26
	v_readlane_b32 s17, v251, 27
	v_readlane_b32 s18, v251, 28
	v_readlane_b32 s19, v251, 29
	s_mov_b64 s[56:57], s[4:5]
	s_branch .LBB0_484
.Ltr_7:
	s_branch .LBB0_7
.Ltr_733:
	s_branch .LBB0_733
.Ltr_734:
	s_branch .LBB0_734
.Ltr_75:
	s_branch .LBB0_75
.Ltr_76:
	s_branch .LBB0_76
.Ltr_8:
	s_branch .LBB0_8
.LBB0_482:
	v_readlane_b32 s0, v251, 14
	v_readlane_b32 s1, v251, 15
	v_readlane_b32 s2, v251, 16
	v_readlane_b32 s3, v251, 17
	v_readlane_b32 s4, v251, 18
	v_readlane_b32 s5, v251, 19
	s_mov_b64 s[20:21], 0x400
	v_readlane_b32 s6, v251, 20
	v_readlane_b32 s7, v251, 21
	v_readlane_b32 s8, v251, 22
	v_readlane_b32 s9, v251, 23
	v_readlane_b32 s10, v251, 24
	v_readlane_b32 s11, v251, 25
	v_readlane_b32 s12, v251, 26
	v_readlane_b32 s13, v251, 27
	v_readlane_b32 s14, v251, 28
	v_readlane_b32 s15, v251, 29
	s_mov_b64 s[56:57], s[0:1]
	s_mov_b64 s[2:3], s[46:47]
	s_movk_i32 s28, 0x400
	s_mov_b64 s[54:55], s[4:5]
